# scan patch + K-loops: setprio flips deleted, static s_setprio 1 for waves 0-3 during each K-loop
# speedup vs baseline: 1.0053x; 1.0002x over previous
.LBB0_131:
	s_ashr_i32 s25, s24, 31
	s_lshl_b64 s[26:27], s[24:25], 21
	s_add_u32 s26, s46, s26
	s_addc_u32 s27, s47, s27
	s_and_b64 s[28:29], s[44:45], exec
	s_cselect_b32 s25, s27, s35
	s_cselect_b32 s61, s26, s34
	s_ashr_i32 s23, s22, 31
	s_lshl_b64 s[28:29], s[22:23], 21
	s_add_u32 s28, s48, s28
	s_addc_u32 s29, s49, s29
	s_and_b64 s[40:41], s[44:45], exec
	s_cselect_b32 s23, s29, s37
	s_cselect_b32 s62, s28, s36
	s_add_u32 s34, s34, 0x100080
	s_addc_u32 s35, s35, 0
	s_add_u32 s63, s36, 0x100
	v_mov_b32_e32 v42, 0
	s_addc_u32 s66, s37, 0
	s_mov_b32 s67, -2
	v_mov_b32_e32 v43, v42
	v_mov_b32_e32 v44, v42
	v_mov_b32_e32 v45, v42
	v_mov_b32_e32 v46, v42
	v_mov_b32_e32 v47, v42
	v_mov_b32_e32 v48, v42
	v_mov_b32_e32 v49, v42
	v_mov_b32_e32 v58, v42
	v_mov_b32_e32 v59, v42
	v_mov_b32_e32 v60, v42
	v_mov_b32_e32 v61, v42
	v_mov_b32_e32 v66, v42
	v_mov_b32_e32 v67, v42
	v_mov_b32_e32 v68, v42
	v_mov_b32_e32 v69, v42
	s_waitcnt vmcnt(0)
	v_mov_b32_e32 v78, v42
	v_mov_b32_e32 v79, v42
	v_mov_b32_e32 v80, v42
	v_mov_b32_e32 v81, v42
	v_mov_b32_e32 v86, v42
	v_mov_b32_e32 v87, v42
	v_mov_b32_e32 v88, v42
	v_mov_b32_e32 v89, v42
	v_mov_b32_e32 v90, v42
	v_mov_b32_e32 v91, v42
	v_mov_b32_e32 v92, v42
	v_mov_b32_e32 v93, v42
	v_mov_b32_e32 v94, v42
	v_mov_b32_e32 v95, v42
	v_mov_b32_e32 v96, v42
	v_mov_b32_e32 v97, v42
	v_mov_b32_e32 v2, v42
	v_mov_b32_e32 v3, v42
	v_mov_b32_e32 v4, v42
	v_mov_b32_e32 v5, v42
	v_mov_b32_e32 v6, v42
	v_mov_b32_e32 v7, v42
	v_mov_b32_e32 v8, v42
	v_mov_b32_e32 v9, v42
	v_mov_b32_e32 v10, v42
	v_mov_b32_e32 v11, v42
	v_mov_b32_e32 v12, v42
	v_mov_b32_e32 v13, v42
	v_mov_b32_e32 v14, v42
	v_mov_b32_e32 v15, v42
	v_mov_b32_e32 v16, v42
	v_mov_b32_e32 v17, v42
	v_mov_b32_e32 v18, v42
	v_mov_b32_e32 v19, v42
	s_waitcnt vmcnt(0)
	v_mov_b32_e32 v20, v42
	v_mov_b32_e32 v21, v42
	v_mov_b32_e32 v22, v42
	v_mov_b32_e32 v23, v42
	v_mov_b32_e32 v24, v42
	v_mov_b32_e32 v25, v42
	v_mov_b32_e32 v26, v42
	v_mov_b32_e32 v27, v42
	v_mov_b32_e32 v28, v42
	v_mov_b32_e32 v29, v42
	v_mov_b32_e32 v30, v42
	v_mov_b32_e32 v31, v42
	v_mov_b32_e32 v32, v42
	v_mov_b32_e32 v33, v42
	v_mov_b32_e32 v98, v42
	v_mov_b32_e32 v99, v42
	v_mov_b32_e32 v100, v42
	v_mov_b32_e32 v101, v42
	v_mov_b32_e32 v102, v42
	v_mov_b32_e32 v103, v42
	v_mov_b32_e32 v104, v42
	v_mov_b32_e32 v105, v42
	v_mov_b32_e32 v106, v42
	v_mov_b32_e32 v107, v42
	v_mov_b32_e32 v108, v42
	v_mov_b32_e32 v109, v42
	v_mov_b32_e32 v110, v42
	v_mov_b32_e32 v111, v42
	v_mov_b32_e32 v112, v42
	v_mov_b32_e32 v113, v42
	v_mov_b32_e32 v114, v42
	v_mov_b32_e32 v115, v42
	v_mov_b32_e32 v116, v42
	v_mov_b32_e32 v117, v42
	v_mov_b32_e32 v118, v42
	v_mov_b32_e32 v119, v42
	v_mov_b32_e32 v120, v42
	v_mov_b32_e32 v121, v42
	v_mov_b32_e32 v122, v42
	v_mov_b32_e32 v123, v42
	v_mov_b32_e32 v124, v42
	v_mov_b32_e32 v125, v42
	v_mov_b32_e32 v126, v42
	v_mov_b32_e32 v127, v42
	v_mov_b32_e32 v128, v42
	v_mov_b32_e32 v129, v42
	v_mov_b32_e32 v34, v42
	v_mov_b32_e32 v35, v42
	v_mov_b32_e32 v36, v42
	v_mov_b32_e32 v37, v42
	v_mov_b32_e32 v38, v42
	v_mov_b32_e32 v39, v42
	v_mov_b32_e32 v40, v42
	v_mov_b32_e32 v41, v42
	v_mov_b32_e32 v50, v42
	v_mov_b32_e32 v51, v42
	v_mov_b32_e32 v52, v42
	v_mov_b32_e32 v53, v42
	v_mov_b32_e32 v54, v42
	v_mov_b32_e32 v55, v42
	v_mov_b32_e32 v56, v42
	v_mov_b32_e32 v57, v42
	v_mov_b32_e32 v62, v42
	v_mov_b32_e32 v63, v42
	v_mov_b32_e32 v64, v42
	v_mov_b32_e32 v65, v42
	v_mov_b32_e32 v70, v42
	v_mov_b32_e32 v71, v42
	v_mov_b32_e32 v72, v42
	v_mov_b32_e32 v73, v42
	v_mov_b32_e32 v74, v42
	v_mov_b32_e32 v75, v42
	v_mov_b32_e32 v76, v42
	v_mov_b32_e32 v77, v42
	v_mov_b32_e32 v82, v42
	v_mov_b32_e32 v83, v42
	v_mov_b32_e32 v84, v42
	v_mov_b32_e32 v85, v42
	v_readfirstlane_b32 s100, v0
	s_cmp_ge_u32 s100, 0x100
	s_cbranch_scc1 .Lprio_skip_132
	s_setprio 1

.LBB0_871:
	s_ashr_i32 s13, s12, 31
	s_lshl_b64 s[16:17], s[12:13], 21
	s_add_u32 s16, s34, s16
	s_addc_u32 s17, s35, s17
	s_and_b64 s[22:23], s[42:43], exec
	s_cselect_b32 s13, s17, s25
	s_cselect_b32 s51, s16, s24
	s_ashr_i32 s9, s8, 31
	s_lshl_b64 s[22:23], s[8:9], 21
	s_add_u32 s22, s36, s22
	s_addc_u32 s23, s37, s23
	s_and_b64 s[28:29], s[42:43], exec
	s_cselect_b32 s9, s23, s27
	s_cselect_b32 s52, s22, s26
	s_add_u32 s24, s24, 0x100080
	s_addc_u32 s25, s25, 0
	s_add_u32 s53, s26, 0x100
	v_mov_b32_e32 v2, 0
	s_addc_u32 s54, s27, 0
	s_mov_b32 s55, -2
	v_mov_b32_e32 v3, v2
	v_mov_b32_e32 v4, v2
	s_waitcnt lgkmcnt(0)
	v_mov_b32_e32 v5, v2
	v_mov_b32_e32 v6, v2
	v_mov_b32_e32 v7, v2
	v_mov_b32_e32 v8, v2
	v_mov_b32_e32 v9, v2
	v_mov_b32_e32 v18, v2
	v_mov_b32_e32 v19, v2
	v_mov_b32_e32 v20, v2
	v_mov_b32_e32 v21, v2
	v_mov_b32_e32 v22, v2
	v_mov_b32_e32 v23, v2
	v_mov_b32_e32 v24, v2
	v_mov_b32_e32 v25, v2
	v_mov_b32_e32 v34, v2
	v_mov_b32_e32 v35, v2
	v_mov_b32_e32 v36, v2
	v_mov_b32_e32 v37, v2
	v_mov_b32_e32 v38, v2
	v_mov_b32_e32 v39, v2
	v_mov_b32_e32 v40, v2
	v_mov_b32_e32 v41, v2
	v_mov_b32_e32 v50, v2
	v_mov_b32_e32 v51, v2
	v_mov_b32_e32 v52, v2
	v_mov_b32_e32 v53, v2
	v_mov_b32_e32 v54, v2
	v_mov_b32_e32 v55, v2
	v_mov_b32_e32 v56, v2
	v_mov_b32_e32 v57, v2
	v_mov_b32_e32 v10, v2
	v_mov_b32_e32 v11, v2
	v_mov_b32_e32 v12, v2
	v_mov_b32_e32 v13, v2
	v_mov_b32_e32 v14, v2
	v_mov_b32_e32 v15, v2
	v_mov_b32_e32 v16, v2
	v_mov_b32_e32 v17, v2
	v_mov_b32_e32 v26, v2
	v_mov_b32_e32 v27, v2
	v_mov_b32_e32 v28, v2
	v_mov_b32_e32 v29, v2
	v_mov_b32_e32 v30, v2
	v_mov_b32_e32 v31, v2
	v_mov_b32_e32 v32, v2
	v_mov_b32_e32 v33, v2
	v_mov_b32_e32 v42, v2
	v_mov_b32_e32 v43, v2
	v_mov_b32_e32 v44, v2
	v_mov_b32_e32 v45, v2
	v_mov_b32_e32 v46, v2
	v_mov_b32_e32 v47, v2
	v_mov_b32_e32 v48, v2
	v_mov_b32_e32 v49, v2
	v_mov_b32_e32 v58, v2
	v_mov_b32_e32 v59, v2
	v_mov_b32_e32 v60, v2
	v_mov_b32_e32 v61, v2
	v_mov_b32_e32 v62, v2
	v_mov_b32_e32 v63, v2
	v_mov_b32_e32 v64, v2
	v_mov_b32_e32 v65, v2
	v_mov_b32_e32 v66, v2
	v_mov_b32_e32 v67, v2
	v_mov_b32_e32 v68, v2
	v_mov_b32_e32 v69, v2
	v_mov_b32_e32 v70, v2
	v_mov_b32_e32 v71, v2
	v_mov_b32_e32 v72, v2
	v_mov_b32_e32 v73, v2
	v_mov_b32_e32 v82, v2
	v_mov_b32_e32 v83, v2
	v_mov_b32_e32 v84, v2
	v_mov_b32_e32 v85, v2
	v_mov_b32_e32 v86, v2
	v_mov_b32_e32 v87, v2
	v_mov_b32_e32 v88, v2
	v_mov_b32_e32 v89, v2
	v_mov_b32_e32 v98, v2
	v_mov_b32_e32 v99, v2
	v_mov_b32_e32 v100, v2
	v_mov_b32_e32 v101, v2
	v_mov_b32_e32 v102, v2
	v_mov_b32_e32 v103, v2
	v_mov_b32_e32 v104, v2
	v_mov_b32_e32 v105, v2
	v_mov_b32_e32 v114, v2
	v_mov_b32_e32 v115, v2
	v_mov_b32_e32 v116, v2
	v_mov_b32_e32 v117, v2
	v_mov_b32_e32 v118, v2
	v_mov_b32_e32 v119, v2
	v_mov_b32_e32 v120, v2
	v_mov_b32_e32 v121, v2
	v_mov_b32_e32 v74, v2
	v_mov_b32_e32 v75, v2
	v_mov_b32_e32 v76, v2
	v_mov_b32_e32 v77, v2
	v_mov_b32_e32 v78, v2
	v_mov_b32_e32 v79, v2
	v_mov_b32_e32 v80, v2
	v_mov_b32_e32 v81, v2
	v_mov_b32_e32 v90, v2
	v_mov_b32_e32 v91, v2
	v_mov_b32_e32 v92, v2
	v_mov_b32_e32 v93, v2
	v_mov_b32_e32 v94, v2
	v_mov_b32_e32 v95, v2
	v_mov_b32_e32 v96, v2
	v_mov_b32_e32 v97, v2
	v_mov_b32_e32 v106, v2
	v_mov_b32_e32 v107, v2
	v_mov_b32_e32 v108, v2
	v_mov_b32_e32 v109, v2
	v_mov_b32_e32 v110, v2
	v_mov_b32_e32 v111, v2
	v_mov_b32_e32 v112, v2
	v_mov_b32_e32 v113, v2
	v_mov_b32_e32 v122, v2
	v_mov_b32_e32 v123, v2
	v_mov_b32_e32 v124, v2
	v_mov_b32_e32 v125, v2
	v_mov_b32_e32 v126, v2
	v_mov_b32_e32 v127, v2
	v_mov_b32_e32 v128, v2
	v_mov_b32_e32 v129, v2
	v_readfirstlane_b32 s100, v0
	s_cmp_ge_u32 s100, 0x100
	s_cbranch_scc1 .Lprio_skip_872
	s_setprio 1

.LBB0_1023:
	s_ashr_i32 s53, s52, 31
	s_lshl_b64 s[54:55], s[52:53], 21
	s_add_u32 s54, s60, s54
	s_addc_u32 s55, s61, s55
	s_and_b64 s[56:57], s[44:45], exec
	s_cselect_b32 s30, s55, s3
	s_cselect_b32 s53, s54, s2
	s_ashr_i32 s51, s50, 31
	s_lshl_b64 s[56:57], s[50:51], 21
	s_add_u32 s56, s62, s56
	s_addc_u32 s57, s63, s57
	s_and_b64 s[58:59], s[44:45], exec
	s_cselect_b32 s51, s57, s47
	s_cselect_b32 s79, s56, s46
	s_add_u32 s2, s2, 0x100080
	s_addc_u32 s3, s3, 0
	s_add_u32 s80, s46, 0x100
	v_mov_b32_e32 v2, 0
	s_addc_u32 s81, s47, 0
	s_mov_b32 s82, -2
	v_mov_b32_e32 v3, v2
	v_mov_b32_e32 v4, v2
	v_mov_b32_e32 v5, v2
	v_mov_b32_e32 v10, v2
	v_mov_b32_e32 v11, v2
	v_mov_b32_e32 v12, v2
	v_mov_b32_e32 v13, v2
	s_waitcnt vmcnt(0)
	v_mov_b32_e32 v18, v2
	v_mov_b32_e32 v19, v2
	v_mov_b32_e32 v20, v2
	v_mov_b32_e32 v21, v2
	v_mov_b32_e32 v26, v2
	v_mov_b32_e32 v27, v2
	v_mov_b32_e32 v28, v2
	v_mov_b32_e32 v29, v2
	v_mov_b32_e32 v34, v2
	v_mov_b32_e32 v35, v2
	v_mov_b32_e32 v36, v2
	v_mov_b32_e32 v37, v2
	v_mov_b32_e32 v42, v2
	v_mov_b32_e32 v43, v2
	v_mov_b32_e32 v44, v2
	v_mov_b32_e32 v45, v2
	v_mov_b32_e32 v50, v2
	v_mov_b32_e32 v51, v2
	v_mov_b32_e32 v52, v2
	v_mov_b32_e32 v53, v2
	v_mov_b32_e32 v58, v2
	v_mov_b32_e32 v59, v2
	v_mov_b32_e32 v60, v2
	v_mov_b32_e32 v61, v2
	v_mov_b32_e32 v6, v2
	v_mov_b32_e32 v7, v2
	v_mov_b32_e32 v8, v2
	v_mov_b32_e32 v9, v2
	v_mov_b32_e32 v14, v2
	v_mov_b32_e32 v15, v2
	v_mov_b32_e32 v16, v2
	v_mov_b32_e32 v17, v2
	v_mov_b32_e32 v22, v2
	v_mov_b32_e32 v23, v2
	v_mov_b32_e32 v24, v2
	v_mov_b32_e32 v25, v2
	v_mov_b32_e32 v30, v2
	v_mov_b32_e32 v31, v2
	v_mov_b32_e32 v32, v2
	v_mov_b32_e32 v33, v2
	v_mov_b32_e32 v38, v2
	v_mov_b32_e32 v39, v2
	v_mov_b32_e32 v40, v2
	v_mov_b32_e32 v41, v2
	v_mov_b32_e32 v46, v2
	v_mov_b32_e32 v47, v2
	v_mov_b32_e32 v48, v2
	v_mov_b32_e32 v49, v2
	v_mov_b32_e32 v54, v2
	v_mov_b32_e32 v55, v2
	v_mov_b32_e32 v56, v2
	v_mov_b32_e32 v57, v2
	v_mov_b32_e32 v86, v2
	v_mov_b32_e32 v87, v2
	v_mov_b32_e32 v88, v2
	v_mov_b32_e32 v89, v2
	v_mov_b32_e32 v114, v2
	v_mov_b32_e32 v115, v2
	v_mov_b32_e32 v116, v2
	v_mov_b32_e32 v117, v2
	v_mov_b32_e32 v122, v2
	v_mov_b32_e32 v123, v2
	v_mov_b32_e32 v124, v2
	v_mov_b32_e32 v125, v2
	v_mov_b32_e32 v132, v2
	v_mov_b32_e32 v133, v2
	v_mov_b32_e32 v134, v2
	v_mov_b32_e32 v135, v2
	v_mov_b32_e32 v140, v2
	v_mov_b32_e32 v141, v2
	v_mov_b32_e32 v142, v2
	v_mov_b32_e32 v143, v2
	v_mov_b32_e32 v148, v2
	v_mov_b32_e32 v149, v2
	v_mov_b32_e32 v150, v2
	v_mov_b32_e32 v151, v2
	v_mov_b32_e32 v156, v2
	v_mov_b32_e32 v157, v2
	v_mov_b32_e32 v158, v2
	v_mov_b32_e32 v159, v2
	v_mov_b32_e32 v164, v2
	v_mov_b32_e32 v165, v2
	v_mov_b32_e32 v166, v2
	v_mov_b32_e32 v167, v2
	v_mov_b32_e32 v172, v2
	v_mov_b32_e32 v173, v2
	v_mov_b32_e32 v174, v2
	v_mov_b32_e32 v175, v2
	v_mov_b32_e32 v118, v2
	v_mov_b32_e32 v119, v2
	v_mov_b32_e32 v120, v2
	v_mov_b32_e32 v121, v2
	v_mov_b32_e32 v126, v2
	v_mov_b32_e32 v127, v2
	v_mov_b32_e32 v128, v2
	v_mov_b32_e32 v129, v2
	v_mov_b32_e32 v136, v2
	v_mov_b32_e32 v137, v2
	v_mov_b32_e32 v138, v2
	v_mov_b32_e32 v139, v2
	v_mov_b32_e32 v144, v2
	v_mov_b32_e32 v145, v2
	v_mov_b32_e32 v146, v2
	v_mov_b32_e32 v147, v2
	v_mov_b32_e32 v152, v2
	v_mov_b32_e32 v153, v2
	v_mov_b32_e32 v154, v2
	v_mov_b32_e32 v155, v2
	v_mov_b32_e32 v160, v2
	v_mov_b32_e32 v161, v2
	v_mov_b32_e32 v162, v2
	v_mov_b32_e32 v163, v2
	v_mov_b32_e32 v168, v2
	v_mov_b32_e32 v169, v2
	v_mov_b32_e32 v170, v2
	v_mov_b32_e32 v171, v2
	v_mov_b32_e32 v176, v2
	v_mov_b32_e32 v177, v2
	v_mov_b32_e32 v178, v2
	v_mov_b32_e32 v179, v2
	v_readfirstlane_b32 s100, v0
	s_cmp_ge_u32 s100, 0x100
	s_cbranch_scc1 .Lprio_skip_1024
	s_setprio 1

.LBB0_1327:
	s_add_u32 s54, s24, 0x100
	v_mov_b32_e32 v2, 0
	s_addc_u32 s55, s25, 0
	s_mov_b32 s56, -2
	v_mov_b32_e32 v3, v2
	v_mov_b32_e32 v4, v2
	v_mov_b32_e32 v5, v2
	v_mov_b32_e32 v6, v2
	v_mov_b32_e32 v7, v2
	v_mov_b32_e32 v8, v2
	v_mov_b32_e32 v9, v2
	v_mov_b32_e32 v18, v2
	v_mov_b32_e32 v19, v2
	v_mov_b32_e32 v20, v2
	v_mov_b32_e32 v21, v2
	v_mov_b32_e32 v22, v2
	v_mov_b32_e32 v23, v2
	v_mov_b32_e32 v24, v2
	v_mov_b32_e32 v25, v2
	s_waitcnt vmcnt(0)
	v_mov_b32_e32 v34, v2
	v_mov_b32_e32 v35, v2
	v_mov_b32_e32 v36, v2
	v_mov_b32_e32 v37, v2
	v_mov_b32_e32 v38, v2
	v_mov_b32_e32 v39, v2
	v_mov_b32_e32 v40, v2
	v_mov_b32_e32 v41, v2
	v_mov_b32_e32 v50, v2
	v_mov_b32_e32 v51, v2
	v_mov_b32_e32 v52, v2
	v_mov_b32_e32 v53, v2
	v_mov_b32_e32 v54, v2
	v_mov_b32_e32 v55, v2
	v_mov_b32_e32 v56, v2
	v_mov_b32_e32 v57, v2
	v_mov_b32_e32 v10, v2
	v_mov_b32_e32 v11, v2
	v_mov_b32_e32 v12, v2
	v_mov_b32_e32 v13, v2
	v_mov_b32_e32 v14, v2
	v_mov_b32_e32 v15, v2
	v_mov_b32_e32 v16, v2
	v_mov_b32_e32 v17, v2
	v_mov_b32_e32 v26, v2
	v_mov_b32_e32 v27, v2
	v_mov_b32_e32 v28, v2
	v_mov_b32_e32 v29, v2
	v_mov_b32_e32 v30, v2
	v_mov_b32_e32 v31, v2
	v_mov_b32_e32 v32, v2
	v_mov_b32_e32 v33, v2
	v_mov_b32_e32 v42, v2
	v_mov_b32_e32 v43, v2
	v_mov_b32_e32 v44, v2
	v_mov_b32_e32 v45, v2
	v_mov_b32_e32 v46, v2
	v_mov_b32_e32 v47, v2
	v_mov_b32_e32 v48, v2
	v_mov_b32_e32 v49, v2
	v_mov_b32_e32 v58, v2
	v_mov_b32_e32 v59, v2
	v_mov_b32_e32 v60, v2
	v_mov_b32_e32 v61, v2
	v_mov_b32_e32 v62, v2
	v_mov_b32_e32 v63, v2
	v_mov_b32_e32 v64, v2
	v_mov_b32_e32 v65, v2
	v_mov_b32_e32 v66, v2
	v_mov_b32_e32 v67, v2
	v_mov_b32_e32 v68, v2
	v_mov_b32_e32 v69, v2
	v_mov_b32_e32 v70, v2
	v_mov_b32_e32 v71, v2
	v_mov_b32_e32 v72, v2
	v_mov_b32_e32 v73, v2
	v_mov_b32_e32 v82, v2
	v_mov_b32_e32 v83, v2
	v_mov_b32_e32 v84, v2
	v_mov_b32_e32 v85, v2
	v_mov_b32_e32 v86, v2
	v_mov_b32_e32 v87, v2
	v_mov_b32_e32 v88, v2
	v_mov_b32_e32 v89, v2
	v_mov_b32_e32 v98, v2
	v_mov_b32_e32 v99, v2
	v_mov_b32_e32 v100, v2
	v_mov_b32_e32 v101, v2
	v_mov_b32_e32 v102, v2
	v_mov_b32_e32 v103, v2
	v_mov_b32_e32 v104, v2
	v_mov_b32_e32 v105, v2
	v_mov_b32_e32 v114, v2
	v_mov_b32_e32 v115, v2
	v_mov_b32_e32 v116, v2
	v_mov_b32_e32 v117, v2
	v_mov_b32_e32 v118, v2
	v_mov_b32_e32 v119, v2
	v_mov_b32_e32 v120, v2
	v_mov_b32_e32 v121, v2
	v_mov_b32_e32 v74, v2
	v_mov_b32_e32 v75, v2
	v_mov_b32_e32 v76, v2
	v_mov_b32_e32 v77, v2
	v_mov_b32_e32 v78, v2
	v_mov_b32_e32 v79, v2
	v_mov_b32_e32 v80, v2
	v_mov_b32_e32 v81, v2
	v_mov_b32_e32 v90, v2
	v_mov_b32_e32 v91, v2
	v_mov_b32_e32 v92, v2
	v_mov_b32_e32 v93, v2
	v_mov_b32_e32 v94, v2
	v_mov_b32_e32 v95, v2
	v_mov_b32_e32 v96, v2
	v_mov_b32_e32 v97, v2
	v_mov_b32_e32 v106, v2
	v_mov_b32_e32 v107, v2
	v_mov_b32_e32 v108, v2
	v_mov_b32_e32 v109, v2
	v_mov_b32_e32 v110, v2
	v_mov_b32_e32 v111, v2
	v_mov_b32_e32 v112, v2
	v_mov_b32_e32 v113, v2
	v_mov_b32_e32 v122, v2
	v_mov_b32_e32 v123, v2
	v_mov_b32_e32 v124, v2
	v_mov_b32_e32 v125, v2
	v_mov_b32_e32 v126, v2
	v_mov_b32_e32 v127, v2
	v_mov_b32_e32 v128, v2
	v_mov_b32_e32 v129, v2
	v_readfirstlane_b32 s100, v0
	s_cmp_ge_u32 s100, 0x100
	s_cbranch_scc1 .Lprio_skip_1328
	s_setprio 1

.LBB0_1353:
	s_add_u32 s57, s24, 0x100
	v_mov_b32_e32 v2, 0
	s_addc_u32 s58, s25, 0
	s_mov_b32 s59, -2
	v_mov_b32_e32 v3, v2
	v_mov_b32_e32 v4, v2
	v_mov_b32_e32 v5, v2
	v_mov_b32_e32 v6, v2
	v_mov_b32_e32 v7, v2
	v_mov_b32_e32 v8, v2
	v_mov_b32_e32 v9, v2
	v_mov_b32_e32 v18, v2
	v_mov_b32_e32 v19, v2
	v_mov_b32_e32 v20, v2
	v_mov_b32_e32 v21, v2
	v_mov_b32_e32 v22, v2
	v_mov_b32_e32 v23, v2
	v_mov_b32_e32 v24, v2
	v_mov_b32_e32 v25, v2
	s_waitcnt vmcnt(0)
	v_mov_b32_e32 v34, v2
	v_mov_b32_e32 v35, v2
	v_mov_b32_e32 v36, v2
	v_mov_b32_e32 v37, v2
	v_mov_b32_e32 v38, v2
	v_mov_b32_e32 v39, v2
	v_mov_b32_e32 v40, v2
	v_mov_b32_e32 v41, v2
	v_mov_b32_e32 v50, v2
	v_mov_b32_e32 v51, v2
	v_mov_b32_e32 v52, v2
	v_mov_b32_e32 v53, v2
	v_mov_b32_e32 v54, v2
	v_mov_b32_e32 v55, v2
	v_mov_b32_e32 v56, v2
	v_mov_b32_e32 v57, v2
	v_mov_b32_e32 v10, v2
	v_mov_b32_e32 v11, v2
	v_mov_b32_e32 v12, v2
	v_mov_b32_e32 v13, v2
	v_mov_b32_e32 v14, v2
	v_mov_b32_e32 v15, v2
	v_mov_b32_e32 v16, v2
	v_mov_b32_e32 v17, v2
	v_mov_b32_e32 v26, v2
	v_mov_b32_e32 v27, v2
	v_mov_b32_e32 v28, v2
	v_mov_b32_e32 v29, v2
	v_mov_b32_e32 v30, v2
	v_mov_b32_e32 v31, v2
	v_mov_b32_e32 v32, v2
	v_mov_b32_e32 v33, v2
	v_mov_b32_e32 v42, v2
	v_mov_b32_e32 v43, v2
	v_mov_b32_e32 v44, v2
	v_mov_b32_e32 v45, v2
	v_mov_b32_e32 v46, v2
	v_mov_b32_e32 v47, v2
	v_mov_b32_e32 v48, v2
	v_mov_b32_e32 v49, v2
	v_mov_b32_e32 v58, v2
	v_mov_b32_e32 v59, v2
	v_mov_b32_e32 v60, v2
	v_mov_b32_e32 v61, v2
	v_mov_b32_e32 v62, v2
	v_mov_b32_e32 v63, v2
	v_mov_b32_e32 v64, v2
	v_mov_b32_e32 v65, v2
	v_mov_b32_e32 v66, v2
	v_mov_b32_e32 v67, v2
	v_mov_b32_e32 v68, v2
	v_mov_b32_e32 v69, v2
	v_mov_b32_e32 v70, v2
	v_mov_b32_e32 v71, v2
	v_mov_b32_e32 v72, v2
	v_mov_b32_e32 v73, v2
	v_mov_b32_e32 v82, v2
	v_mov_b32_e32 v83, v2
	v_mov_b32_e32 v84, v2
	v_mov_b32_e32 v85, v2
	v_mov_b32_e32 v86, v2
	v_mov_b32_e32 v87, v2
	v_mov_b32_e32 v88, v2
	v_mov_b32_e32 v89, v2
	v_mov_b32_e32 v98, v2
	v_mov_b32_e32 v99, v2
	v_mov_b32_e32 v100, v2
	v_mov_b32_e32 v101, v2
	v_mov_b32_e32 v102, v2
	v_mov_b32_e32 v103, v2
	v_mov_b32_e32 v104, v2
	v_mov_b32_e32 v105, v2
	v_mov_b32_e32 v114, v2
	v_mov_b32_e32 v115, v2
	v_mov_b32_e32 v116, v2
	v_mov_b32_e32 v117, v2
	v_mov_b32_e32 v118, v2
	v_mov_b32_e32 v119, v2
	v_mov_b32_e32 v120, v2
	v_mov_b32_e32 v121, v2
	v_mov_b32_e32 v74, v2
	v_mov_b32_e32 v75, v2
	v_mov_b32_e32 v76, v2
	v_mov_b32_e32 v77, v2
	v_mov_b32_e32 v78, v2
	v_mov_b32_e32 v79, v2
	v_mov_b32_e32 v80, v2
	v_mov_b32_e32 v81, v2
	v_mov_b32_e32 v90, v2
	v_mov_b32_e32 v91, v2
	v_mov_b32_e32 v92, v2
	v_mov_b32_e32 v93, v2
	v_mov_b32_e32 v94, v2
	v_mov_b32_e32 v95, v2
	v_mov_b32_e32 v96, v2
	v_mov_b32_e32 v97, v2
	v_mov_b32_e32 v106, v2
	v_mov_b32_e32 v107, v2
	v_mov_b32_e32 v108, v2
	v_mov_b32_e32 v109, v2
	v_mov_b32_e32 v110, v2
	v_mov_b32_e32 v111, v2
	v_mov_b32_e32 v112, v2
	v_mov_b32_e32 v113, v2
	v_mov_b32_e32 v122, v2
	v_mov_b32_e32 v123, v2
	v_mov_b32_e32 v124, v2
	v_mov_b32_e32 v125, v2
	v_mov_b32_e32 v126, v2
	v_mov_b32_e32 v127, v2
	v_mov_b32_e32 v128, v2
	v_mov_b32_e32 v129, v2
	v_readfirstlane_b32 s100, v0
	s_cmp_ge_u32 s100, 0x100
	s_cbranch_scc1 .Lprio_skip_1354
	s_setprio 1

.LBB0_1404:
	s_add_u32 s51, s22, 0x100
	v_mov_b32_e32 v2, 0
	s_addc_u32 s52, s23, 0
	s_mov_b32 s53, -2
	v_mov_b32_e32 v3, v2
	v_mov_b32_e32 v4, v2
	s_waitcnt lgkmcnt(0)
	v_mov_b32_e32 v5, v2
	v_mov_b32_e32 v6, v2
	v_mov_b32_e32 v7, v2
	v_mov_b32_e32 v8, v2
	v_mov_b32_e32 v9, v2
	v_mov_b32_e32 v18, v2
	v_mov_b32_e32 v19, v2
	v_mov_b32_e32 v20, v2
	v_mov_b32_e32 v21, v2
	v_mov_b32_e32 v22, v2
	v_mov_b32_e32 v23, v2
	v_mov_b32_e32 v24, v2
	v_mov_b32_e32 v25, v2
	s_waitcnt vmcnt(0)
	v_mov_b32_e32 v34, v2
	v_mov_b32_e32 v35, v2
	v_mov_b32_e32 v36, v2
	v_mov_b32_e32 v37, v2
	v_mov_b32_e32 v38, v2
	v_mov_b32_e32 v39, v2
	v_mov_b32_e32 v40, v2
	v_mov_b32_e32 v41, v2
	v_mov_b32_e32 v50, v2
	v_mov_b32_e32 v51, v2
	v_mov_b32_e32 v52, v2
	v_mov_b32_e32 v53, v2
	v_mov_b32_e32 v54, v2
	v_mov_b32_e32 v55, v2
	v_mov_b32_e32 v56, v2
	v_mov_b32_e32 v57, v2
	v_mov_b32_e32 v10, v2
	v_mov_b32_e32 v11, v2
	v_mov_b32_e32 v12, v2
	v_mov_b32_e32 v13, v2
	v_mov_b32_e32 v14, v2
	v_mov_b32_e32 v15, v2
	v_mov_b32_e32 v16, v2
	v_mov_b32_e32 v17, v2
	v_mov_b32_e32 v26, v2
	v_mov_b32_e32 v27, v2
	v_mov_b32_e32 v28, v2
	v_mov_b32_e32 v29, v2
	v_mov_b32_e32 v30, v2
	v_mov_b32_e32 v31, v2
	v_mov_b32_e32 v32, v2
	v_mov_b32_e32 v33, v2
	v_mov_b32_e32 v42, v2
	v_mov_b32_e32 v43, v2
	v_mov_b32_e32 v44, v2
	v_mov_b32_e32 v45, v2
	v_mov_b32_e32 v46, v2
	v_mov_b32_e32 v47, v2
	v_mov_b32_e32 v48, v2
	v_mov_b32_e32 v49, v2
	v_mov_b32_e32 v58, v2
	v_mov_b32_e32 v59, v2
	v_mov_b32_e32 v60, v2
	v_mov_b32_e32 v61, v2
	v_mov_b32_e32 v62, v2
	v_mov_b32_e32 v63, v2
	v_mov_b32_e32 v64, v2
	v_mov_b32_e32 v65, v2
	v_mov_b32_e32 v66, v2
	v_mov_b32_e32 v67, v2
	v_mov_b32_e32 v68, v2
	v_mov_b32_e32 v69, v2
	v_mov_b32_e32 v70, v2
	v_mov_b32_e32 v71, v2
	v_mov_b32_e32 v72, v2
	v_mov_b32_e32 v73, v2
	v_mov_b32_e32 v82, v2
	v_mov_b32_e32 v83, v2
	v_mov_b32_e32 v84, v2
	v_mov_b32_e32 v85, v2
	v_mov_b32_e32 v86, v2
	v_mov_b32_e32 v87, v2
	v_mov_b32_e32 v88, v2
	v_mov_b32_e32 v89, v2
	v_mov_b32_e32 v98, v2
	v_mov_b32_e32 v99, v2
	v_mov_b32_e32 v100, v2
	v_mov_b32_e32 v101, v2
	v_mov_b32_e32 v102, v2
	v_mov_b32_e32 v103, v2
	v_mov_b32_e32 v104, v2
	v_mov_b32_e32 v105, v2
	v_mov_b32_e32 v114, v2
	v_mov_b32_e32 v115, v2
	v_mov_b32_e32 v116, v2
	v_mov_b32_e32 v117, v2
	v_mov_b32_e32 v118, v2
	v_mov_b32_e32 v119, v2
	v_mov_b32_e32 v120, v2
	v_mov_b32_e32 v121, v2
	v_mov_b32_e32 v74, v2
	v_mov_b32_e32 v75, v2
	v_mov_b32_e32 v76, v2
	v_mov_b32_e32 v77, v2
	v_mov_b32_e32 v78, v2
	v_mov_b32_e32 v79, v2
	v_mov_b32_e32 v80, v2
	v_mov_b32_e32 v81, v2
	v_mov_b32_e32 v90, v2
	v_mov_b32_e32 v91, v2
	v_mov_b32_e32 v92, v2
	v_mov_b32_e32 v93, v2
	v_mov_b32_e32 v94, v2
	v_mov_b32_e32 v95, v2
	v_mov_b32_e32 v96, v2
	v_mov_b32_e32 v97, v2
	v_mov_b32_e32 v106, v2
	v_mov_b32_e32 v107, v2
	v_mov_b32_e32 v108, v2
	v_mov_b32_e32 v109, v2
	v_mov_b32_e32 v110, v2
	v_mov_b32_e32 v111, v2
	v_mov_b32_e32 v112, v2
	v_mov_b32_e32 v113, v2
	v_mov_b32_e32 v122, v2
	v_mov_b32_e32 v123, v2
	v_mov_b32_e32 v124, v2
	v_mov_b32_e32 v125, v2
	v_mov_b32_e32 v126, v2
	v_mov_b32_e32 v127, v2
	v_mov_b32_e32 v128, v2
	v_mov_b32_e32 v129, v2
	v_readfirstlane_b32 s100, v0
	s_cmp_ge_u32 s100, 0x100
	s_cbranch_scc1 .Lprio_skip_1405
	s_setprio 1
